# final RMSNorm: the 8 loop-invariant weight vectors loaded once before the row loop instead of 7 serialised reloads per row
# speedup vs baseline: 1.0040x; 1.0040x over previous
; DEVI void phase_final_norm(float* x, const float* gain, int bid, int nb) {
;     int tid_ = threadIdx.x; asm volatile("" : "+v"(tid_));
;     const int wid = tid_ >> 6, lane = tid_ & 63;
;     for (int row = bid * 8 + wid; row < S; row += nb * 8) {
;         f32x4* xr = (f32x4*)(x + (size_t)row * D);
;         f32x4 v[8]; float ss = 0.f;
; #pragma unroll
;         for (int i = 0; i < 8; ++i) { v[i] = xr[lane + 64 * i]; ss += v[i][0] * v[i][0] + v[i][1] * v[i][1] + v[i][2] * v[i][2] + v[i][3] * v[i][3]; }
;         ss = wave_sum(ss);
;         const float r = rsqrtf(ss * (1.0f / D) + 1e-6f);
; #pragma unroll
;         for (int i = 0; i < 8; ++i) xr[lane + 64 * i] = v[i] * r * ((const f32x4*)gain)[lane + 64 * i];
.LBB0_1004:
	v_readlane_b32 s4, v255, 26
	v_ashrrev_i32_e32 v10, 6, v199
	s_movk_i32 s0, 0x4000
	v_add_u32_e32 v12, s4, v10
	v_readlane_b32 s5, v255, 27
	v_cmp_gt_i32_e32 vcc, s0, v12
	s_and_saveexec_b64 s[0:1], vcc
	s_cbranch_execz .LBB0_1007
	v_cmp_lt_i32_e32 vcc, v209, v203
	v_ashrrev_i32_e32 v11, 31, v10
	v_lshl_add_u64 v[10:11], v[10:11], 0, s[4:5]
	v_cndmask_b32_e32 v0, v202, v209, vcc
	v_cmp_lt_i32_e32 vcc, v208, v203
	v_lshlrev_b32_e32 v13, 2, v0
	v_mov_b32_e32 v21, 0
	v_cndmask_b32_e32 v0, v202, v208, vcc
	v_cmp_lt_i32_e32 vcc, v200, v203
	v_lshlrev_b32_e32 v14, 2, v0
	v_readlane_b32 s0, v252, 0
	v_cndmask_b32_e32 v0, v202, v200, vcc
	v_cmp_lt_i32_e32 vcc, v211, v203
	v_lshlrev_b32_e32 v15, 2, v0
	v_lshlrev_b64 v[10:11], 13, v[10:11]
	v_cndmask_b32_e32 v0, v202, v211, vcc
	v_cmp_lt_i32_e32 vcc, v205, v203
	v_lshlrev_b32_e32 v16, 2, v0
	v_readlane_b32 s1, v252, 1
	v_cndmask_b32_e32 v0, v202, v205, vcc
	v_cmp_lt_i32_e32 vcc, v204, v203
	v_lshlrev_b32_e32 v17, 2, v0
	v_readlane_b32 s2, v252, 2
	v_cndmask_b32_e32 v0, v202, v204, vcc
	v_lshlrev_b32_e32 v18, 2, v0
	v_lshlrev_b32_e32 v0, 4, v199
	v_and_b32_e32 v20, 0x3f0, v0
	v_readlane_b32 s3, v252, 3
	v_or_b32_e32 v2, 0x1000, v20
	v_mov_b32_e32 v3, v21
	v_or_b32_e32 v4, 0x1400, v20
	v_mov_b32_e32 v5, v21
	v_or_b32_e32 v6, 0x1800, v20
	v_mov_b32_e32 v7, v21
	v_or_b32_e32 v8, 0x1c00, v20
	v_mov_b32_e32 v9, v21
	v_or_b32_e32 v10, v10, v20
	v_lshl_add_u64 v[0:1], s[0:1], 0, v[20:21]
	v_lshl_add_u64 v[2:3], s[0:1], 0, v[2:3]
	v_lshl_add_u64 v[4:5], s[0:1], 0, v[4:5]
	v_lshl_add_u64 v[6:7], s[0:1], 0, v[6:7]
	v_lshl_add_u64 v[8:9], s[0:1], 0, v[8:9]
	v_lshl_add_u64 v[10:11], s[2:3], 0, v[10:11]
	s_mov_b64 s[0:1], 0x1000
	v_lshl_add_u64 v[10:11], v[10:11], 0, s[0:1]
	s_mov_b64 s[0:1], 0
	v_mov_b32_e32 v19, 0x358637bd
	s_mov_b32 s2, 0x800000
	s_movk_i32 s3, 0x3fff
	global_load_dwordx4 v[220:223], v[0:1], off
	global_load_dwordx4 v[224:227], v[0:1], off offset:1024
	global_load_dwordx4 v[228:231], v[0:1], off offset:2048
	global_load_dwordx4 v[232:235], v[0:1], off offset:3072
	global_load_dwordx4 v[236:239], v[2:3], off
	global_load_dwordx4 v[240:243], v[4:5], off
	global_load_dwordx4 v[244:247], v[6:7], off
	global_load_dwordx4 v[248:251], v[8:9], off
; DEVI void phase_final_norm(float* x, const float* gain, int bid, int nb) {
;     ...
;     for (int row = bid * 8 + wid; row < S; row += nb * 8) {
;         f32x4* xr = (f32x4*)(x + (size_t)row * D);
;         f32x4 v[8]; float ss = 0.f;
; #pragma unroll
;         for (int i = 0; i < 8; ++i) { v[i] = xr[lane + 64 * i]; ss += v[i][0] * v[i][0] + v[i][1] * v[i][1] + v[i][2] * v[i][2] + v[i][3] * v[i][3]; }
;         ss = wave_sum(ss);
;         const float r = rsqrtf(ss * (1.0f / D) + 1e-6f);
; #pragma unroll
;         for (int i = 0; i < 8; ++i) xr[lane + 64 * i] = v[i] * r * ((const f32x4*)gain)[lane + 64 * i];
.LBB0_1006:
	global_load_dwordx4 v[20:23], v[10:11], off offset:-4096
	global_load_dwordx4 v[24:27], v[10:11], off offset:-3072
	global_load_dwordx4 v[28:31], v[10:11], off offset:-2048
	global_load_dwordx4 v[32:35], v[10:11], off offset:-1024
	global_load_dwordx4 v[36:39], v[10:11], off
	global_load_dwordx4 v[40:43], v[10:11], off offset:1024
	global_load_dwordx4 v[44:47], v[10:11], off offset:2048
	global_load_dwordx4 v[48:51], v[10:11], off offset:3072
	v_add_u32_e32 v12, s78, v12
	s_waitcnt vmcnt(7)
	v_mul_f32_e32 v72, v21, v21
	s_waitcnt vmcnt(6)
	v_mul_f32_e32 v73, v25, v25
	s_waitcnt vmcnt(5)
	v_mul_f32_e32 v74, v29, v29
	v_fmac_f32_e32 v72, v20, v20
	s_waitcnt vmcnt(3)
	v_mov_b32_e32 v58, v37
	s_waitcnt vmcnt(2)
	v_mov_b32_e32 v59, v41
	v_fmac_f32_e32 v73, v24, v24
	v_mul_f32_e32 v75, v33, v33
	v_mov_b32_e32 v56, v36
	v_mov_b32_e32 v57, v40
	v_pk_mul_f32 v[58:59], v[58:59], v[58:59]
	v_fmac_f32_e32 v74, v28, v28
	v_fmac_f32_e32 v72, v22, v22
	v_fmac_f32_e32 v73, v26, v26
	v_mov_b32_e32 v60, v38
	v_mov_b32_e32 v61, v42
	v_fmac_f32_e32 v75, v32, v32
	v_pk_fma_f32 v[56:57], v[56:57], v[56:57], v[58:59]
	v_fmac_f32_e32 v74, v30, v30
	v_fmac_f32_e32 v72, v23, v23
	v_fmac_f32_e32 v73, v27, v27
	s_waitcnt vmcnt(1)
	v_mov_b32_e32 v64, v45
	s_waitcnt vmcnt(0)
	v_mov_b32_e32 v65, v49
	v_fmac_f32_e32 v75, v34, v34
	v_pk_fma_f32 v[56:57], v[60:61], v[60:61], v[56:57]
	v_fmac_f32_e32 v74, v31, v31
	v_add_f32_e32 v60, v72, v73
	v_mov_b32_e32 v62, v44
	v_mov_b32_e32 v63, v48
	v_mov_b32_e32 v66, v39
	v_mov_b32_e32 v67, v43
	v_pk_mul_f32 v[64:65], v[64:65], v[64:65]
	v_fmac_f32_e32 v75, v35, v35
	v_add_f32_e32 v60, v60, v74
	v_mov_b32_e32 v68, v46
	v_mov_b32_e32 v69, v50
	v_pk_fma_f32 v[58:59], v[62:63], v[62:63], v[64:65]
	v_pk_fma_f32 v[56:57], v[66:67], v[66:67], v[56:57]
	v_add_f32_e32 v60, v60, v75
	v_mov_b32_e32 v70, v47
	v_mov_b32_e32 v71, v51
	v_pk_fma_f32 v[58:59], v[68:69], v[68:69], v[58:59]
	v_add_f32_e32 v56, v60, v56
	v_pk_fma_f32 v[58:59], v[70:71], v[70:71], v[58:59]
	v_add_f32_e32 v56, v56, v57
	v_add_f32_e32 v56, v56, v58
	v_add_f32_e32 v56, v56, v59
	ds_bpermute_b32 v57, v13, v56
	s_waitcnt lgkmcnt(0)
	v_add_f32_e32 v56, v56, v57
	ds_bpermute_b32 v57, v14, v56
	s_waitcnt lgkmcnt(0)
	v_add_f32_e32 v56, v56, v57
	ds_bpermute_b32 v57, v15, v56
	s_waitcnt lgkmcnt(0)
	v_add_f32_e32 v56, v56, v57
	ds_bpermute_b32 v57, v16, v56
	s_waitcnt lgkmcnt(0)
	v_add_f32_e32 v56, v56, v57
	ds_bpermute_b32 v57, v17, v56
	s_waitcnt lgkmcnt(0)
	v_add_f32_e32 v56, v56, v57
	ds_bpermute_b32 v57, v18, v56
	s_waitcnt lgkmcnt(0)
	v_add_f32_e32 v56, v56, v57
	v_fmamk_f32 v56, v56, 0x3a000000, v19
	v_mul_f32_e32 v57, 0x4b800000, v56
	v_cmp_gt_f32_e32 vcc, s2, v56
	s_nop 1
	v_cndmask_b32_e32 v56, v56, v57, vcc
	v_rsq_f32_e32 v56, v56
	s_nop 0
	v_mul_f32_e32 v57, 0x45800000, v56
	v_cndmask_b32_e32 v56, v56, v57, vcc
	v_pk_mul_f32 v[20:21], v[20:21], v[56:57] op_sel_hi:[1,0]
	v_pk_mul_f32 v[22:23], v[22:23], v[56:57] op_sel_hi:[1,0]
	v_pk_mul_f32 v[20:21], v[220:221], v[20:21]
	v_pk_mul_f32 v[22:23], v[222:223], v[22:23]
	global_store_dwordx4 v[10:11], v[20:23], off offset:-4096
	v_pk_mul_f32 v[26:27], v[26:27], v[56:57] op_sel_hi:[1,0]
	v_pk_mul_f32 v[24:25], v[24:25], v[56:57] op_sel_hi:[1,0]
	v_cmp_lt_i32_e32 vcc, s3, v12
	s_or_b64 s[0:1], vcc, s[0:1]
	v_pk_mul_f32 v[20:21], v[224:225], v[24:25]
	v_pk_mul_f32 v[22:23], v[226:227], v[26:27]
	global_store_dwordx4 v[10:11], v[20:23], off offset:-3072
	v_pk_mul_f32 v[24:25], v[30:31], v[56:57] op_sel_hi:[1,0]
	v_pk_mul_f32 v[26:27], v[28:29], v[56:57] op_sel_hi:[1,0]
	v_pk_mul_f32 v[22:23], v[230:231], v[24:25]
	v_pk_mul_f32 v[20:21], v[228:229], v[26:27]
	global_store_dwordx4 v[10:11], v[20:23], off offset:-2048
	v_pk_mul_f32 v[24:25], v[34:35], v[56:57] op_sel_hi:[1,0]
	v_pk_mul_f32 v[26:27], v[32:33], v[56:57] op_sel_hi:[1,0]
	v_pk_mul_f32 v[22:23], v[234:235], v[24:25]
	v_pk_mul_f32 v[20:21], v[232:233], v[26:27]
	global_store_dwordx4 v[10:11], v[20:23], off offset:-1024
	v_pk_mul_f32 v[24:25], v[38:39], v[56:57] op_sel_hi:[1,0]
	v_pk_mul_f32 v[26:27], v[36:37], v[56:57] op_sel_hi:[1,0]
	v_pk_mul_f32 v[22:23], v[238:239], v[24:25]
	v_pk_mul_f32 v[20:21], v[236:237], v[26:27]
	global_store_dwordx4 v[10:11], v[20:23], off
	v_pk_mul_f32 v[24:25], v[42:43], v[56:57] op_sel_hi:[1,0]
	v_pk_mul_f32 v[26:27], v[40:41], v[56:57] op_sel_hi:[1,0]
	v_pk_mul_f32 v[22:23], v[242:243], v[24:25]
	v_pk_mul_f32 v[20:21], v[240:241], v[26:27]
	global_store_dwordx4 v[10:11], v[20:23], off offset:1024
	v_pk_mul_f32 v[24:25], v[46:47], v[56:57] op_sel_hi:[1,0]
	v_pk_mul_f32 v[26:27], v[44:45], v[56:57] op_sel_hi:[1,0]
	v_pk_mul_f32 v[22:23], v[246:247], v[24:25]
	v_pk_mul_f32 v[20:21], v[244:245], v[26:27]
	global_store_dwordx4 v[10:11], v[20:23], off offset:2048
	v_pk_mul_f32 v[24:25], v[50:51], v[56:57] op_sel_hi:[1,0]
	v_pk_mul_f32 v[26:27], v[48:49], v[56:57] op_sel_hi:[1,0]
	v_pk_mul_f32 v[22:23], v[250:251], v[24:25]
	v_pk_mul_f32 v[20:21], v[248:249], v[26:27]
	global_store_dwordx4 v[10:11], v[20:23], off offset:3072
	v_lshl_add_u64 v[10:11], v[10:11], 0, s[94:95]
	s_andn2_b64 exec, exec, s[0:1]
	s_cbranch_execnz .LBB0_1006
